# attention PV: filler VALU spread evenly over the MFMA gaps (2 exps per gap, packs behind them, l-sum adds distributed)
# baseline (speedup 1.0000x reference)
.Latt_diff_norescale:
	v_exp_f32_e32 v64, v64
	v_exp_f32_e32 v65, v65
	v_exp_f32_e32 v66, v66
	v_exp_f32_e32 v67, v67
	v_exp_f32_e32 v68, v68
	v_exp_f32_e32 v69, v69
	v_exp_f32_e32 v70, v70
	v_exp_f32_e32 v71, v71
	v_cvt_pk_bf16_f32 v218, v64, v65
	v_cvt_pk_bf16_f32 v219, v66, v67
	v_cvt_pk_bf16_f32 v220, v68, v69
	v_cvt_pk_bf16_f32 v221, v70, v71
	s_waitcnt lgkmcnt(3)
	s_nop 0
	v_mfma_f32_32x32x16_bf16 v[0:15], v[112:115], v[218:221], v[0:15]
	ds_read_b128 v[112:115], v243 offset:27680
	v_exp_f32_e32 v72, v72
	v_exp_f32_e32 v73, v73
	v_add_f32_e32 v226, v64, v68
	s_waitcnt lgkmcnt(3)
	v_mfma_f32_32x32x16_bf16 v[48:63], v[116:119], v[218:221], v[48:63]
	ds_read_b128 v[116:119], v243 offset:32288
	v_exp_f32_e32 v74, v74
	v_exp_f32_e32 v75, v75
	v_cvt_pk_bf16_f32 v222, v72, v73
	v_add_f32_e32 v227, v65, v69
	s_waitcnt lgkmcnt(3)
	v_mfma_f32_32x32x16_bf16 v[32:47], v[120:123], v[218:221], v[32:47]
	ds_read_b128 v[120:123], v243 offset:36896
	v_exp_f32_e32 v76, v76
	v_exp_f32_e32 v77, v77
	v_cvt_pk_bf16_f32 v223, v74, v75
	v_add_f32_e32 v228, v66, v70
	s_waitcnt lgkmcnt(3)
	v_mfma_f32_32x32x16_bf16 v[16:31], v[124:127], v[218:221], v[16:31]
	ds_read_b128 v[124:127], v243 offset:41504
	v_exp_f32_e32 v78, v78
	v_exp_f32_e32 v79, v79
	v_cvt_pk_bf16_f32 v224, v76, v77
	v_cvt_pk_bf16_f32 v225, v78, v79
	v_add_f32_e32 v229, v67, v71
	s_waitcnt lgkmcnt(3)
	v_mfma_f32_32x32x16_bf16 v[0:15], v[112:115], v[222:225], v[0:15]
	ds_read_b128 v[112:115], v243 offset:27712
	v_exp_f32_e32 v80, v80
	v_exp_f32_e32 v81, v81
	v_add_f32_e32 v226, v226, v72
	v_add_f32_e32 v227, v227, v73
	v_add_f32_e32 v228, v228, v74
	s_waitcnt lgkmcnt(3)
	v_mfma_f32_32x32x16_bf16 v[48:63], v[116:119], v[222:225], v[48:63]
	ds_read_b128 v[116:119], v243 offset:32320
	v_exp_f32_e32 v82, v82
	v_exp_f32_e32 v83, v83
	v_cvt_pk_bf16_f32 v218, v80, v81
	v_add_f32_e32 v229, v229, v75
	v_add_f32_e32 v226, v226, v76
	s_waitcnt lgkmcnt(3)
	v_mfma_f32_32x32x16_bf16 v[32:47], v[120:123], v[222:225], v[32:47]
	ds_read_b128 v[120:123], v243 offset:36928
	v_exp_f32_e32 v84, v84
	v_exp_f32_e32 v85, v85
	v_cvt_pk_bf16_f32 v219, v82, v83
	v_add_f32_e32 v227, v227, v77
	v_add_f32_e32 v228, v228, v78
	s_waitcnt lgkmcnt(3)
	v_mfma_f32_32x32x16_bf16 v[16:31], v[124:127], v[222:225], v[16:31]
	ds_read_b128 v[124:127], v243 offset:41536
	v_exp_f32_e32 v86, v86
	v_exp_f32_e32 v87, v87
	v_cvt_pk_bf16_f32 v220, v84, v85
	v_cvt_pk_bf16_f32 v221, v86, v87
	v_add_f32_e32 v229, v229, v79
	s_waitcnt lgkmcnt(3)
	v_mfma_f32_32x32x16_bf16 v[0:15], v[112:115], v[218:221], v[0:15]
	ds_read_b128 v[112:115], v243 offset:27744
	v_exp_f32_e32 v88, v88
	v_exp_f32_e32 v89, v89
	v_add_f32_e32 v226, v226, v80
	v_add_f32_e32 v227, v227, v81
	v_add_f32_e32 v228, v228, v82
	s_waitcnt lgkmcnt(3)
	v_mfma_f32_32x32x16_bf16 v[48:63], v[116:119], v[218:221], v[48:63]
	ds_read_b128 v[116:119], v243 offset:32352
	v_exp_f32_e32 v90, v90
	v_exp_f32_e32 v91, v91
	v_cvt_pk_bf16_f32 v222, v88, v89
	v_add_f32_e32 v229, v229, v83
	v_add_f32_e32 v226, v226, v84
	s_waitcnt lgkmcnt(3)
	v_mfma_f32_32x32x16_bf16 v[32:47], v[120:123], v[218:221], v[32:47]
	ds_read_b128 v[120:123], v243 offset:36960
	v_exp_f32_e32 v92, v92
	v_exp_f32_e32 v93, v93
	v_cvt_pk_bf16_f32 v223, v90, v91
	v_add_f32_e32 v227, v227, v85
	v_add_f32_e32 v228, v228, v86
	s_waitcnt lgkmcnt(3)
	v_mfma_f32_32x32x16_bf16 v[16:31], v[124:127], v[218:221], v[16:31]
	ds_read_b128 v[124:127], v243 offset:41568
	v_exp_f32_e32 v94, v94
	v_exp_f32_e32 v95, v95
	v_cvt_pk_bf16_f32 v224, v92, v93
	v_cvt_pk_bf16_f32 v225, v94, v95
	v_add_f32_e32 v229, v229, v87
	s_waitcnt lgkmcnt(3)
	v_mfma_f32_32x32x16_bf16 v[0:15], v[112:115], v[222:225], v[0:15]
	v_add_f32_e32 v226, v226, v88
	v_add_f32_e32 v227, v227, v89
	s_waitcnt lgkmcnt(2)
	v_mfma_f32_32x32x16_bf16 v[48:63], v[116:119], v[222:225], v[48:63]
	v_add_f32_e32 v228, v228, v90
	v_add_f32_e32 v229, v229, v91
	s_waitcnt lgkmcnt(1)
	v_mfma_f32_32x32x16_bf16 v[32:47], v[120:123], v[222:225], v[32:47]
	v_add_f32_e32 v226, v226, v92
	v_add_f32_e32 v227, v227, v93
	s_waitcnt lgkmcnt(0)
	v_mfma_f32_32x32x16_bf16 v[16:31], v[124:127], v[222:225], v[16:31]
	v_add_f32_e32 v228, v228, v94
	v_add_f32_e32 v229, v229, v95
	v_add_f32_e32 v226, v226, v227
	v_add_f32_e32 v228, v228, v229
	v_add_f32_e32 v226, v226, v228
	v_add_f32_e32 v157, v157, v226

.Latt_mla_norescale:
	v_exp_f32_e32 v64, v64
	v_exp_f32_e32 v65, v65
	v_exp_f32_e32 v66, v66
	v_exp_f32_e32 v67, v67
	v_exp_f32_e32 v68, v68
	v_exp_f32_e32 v69, v69
	v_exp_f32_e32 v70, v70
	v_exp_f32_e32 v71, v71
	v_cvt_pk_bf16_f32 v124, v64, v65
	v_cvt_pk_bf16_f32 v125, v66, v67
	v_cvt_pk_bf16_f32 v126, v68, v69
	v_cvt_pk_bf16_f32 v127, v70, v71
	s_waitcnt lgkmcnt(2)
	s_nop 0
	v_mfma_f32_32x32x16_bf16 v[48:63], v[112:115], v[124:127], v[48:63]
	ds_read_b128 v[112:115], v219 offset:13824
	v_exp_f32_e32 v72, v72
	v_exp_f32_e32 v73, v73
	v_add_f32_e32 v209, v64, v68
	s_waitcnt lgkmcnt(2)
	v_mfma_f32_32x32x16_bf16 v[32:47], v[116:119], v[124:127], v[32:47]
	ds_read_b128 v[116:119], v219 offset:32
	v_exp_f32_e32 v74, v74
	v_exp_f32_e32 v75, v75
	v_cvt_pk_bf16_f32 v250, v72, v73
	v_add_f32_e32 v211, v65, v69
	s_waitcnt lgkmcnt(2)
	v_mfma_f32_32x32x16_bf16 v[16:31], v[120:123], v[124:127], v[16:31]
	ds_read_b128 v[120:123], v219 offset:4640
	v_exp_f32_e32 v76, v76
	v_exp_f32_e32 v77, v77
	v_cvt_pk_bf16_f32 v251, v74, v75
	v_add_f32_e32 v213, v66, v70
	s_waitcnt lgkmcnt(2)
	v_mfma_f32_32x32x16_bf16 v[0:15], v[112:115], v[124:127], v[0:15]
	ds_read_b128 v[112:115], v219 offset:9248
	v_exp_f32_e32 v78, v78
	v_exp_f32_e32 v79, v79
	v_cvt_pk_bf16_f32 v252, v76, v77
	v_cvt_pk_bf16_f32 v253, v78, v79
	v_add_f32_e32 v215, v67, v71
	s_waitcnt lgkmcnt(2)
	v_mfma_f32_32x32x16_bf16 v[48:63], v[116:119], v[250:253], v[48:63]
	ds_read_b128 v[64:67], v219 offset:13856
	ds_read_b128 v[68:71], v219 offset:64
	v_exp_f32_e32 v80, v80
	v_exp_f32_e32 v81, v81
	v_add_f32_e32 v209, v209, v72
	v_add_f32_e32 v211, v211, v73
	v_add_f32_e32 v213, v213, v74
	s_waitcnt lgkmcnt(3)
	v_mfma_f32_32x32x16_bf16 v[32:47], v[120:123], v[250:253], v[32:47]
	ds_read_b128 v[116:119], v219 offset:4672
	ds_read_b128 v[120:123], v219 offset:9280
	v_exp_f32_e32 v82, v82
	v_exp_f32_e32 v83, v83
	v_cvt_pk_bf16_f32 v124, v80, v81
	v_add_f32_e32 v215, v215, v75
	v_add_f32_e32 v209, v209, v76
	s_waitcnt lgkmcnt(4)
	v_mfma_f32_32x32x16_bf16 v[16:31], v[112:115], v[250:253], v[16:31]
	ds_read_b128 v[112:115], v219 offset:13888
	v_exp_f32_e32 v84, v84
	v_exp_f32_e32 v85, v85
	v_cvt_pk_bf16_f32 v125, v82, v83
	v_add_f32_e32 v211, v211, v77
	v_add_f32_e32 v213, v213, v78
	s_waitcnt lgkmcnt(4)
	v_mfma_f32_32x32x16_bf16 v[0:15], v[64:67], v[250:253], v[0:15]
	ds_read_b128 v[64:67], v219 offset:96
	v_exp_f32_e32 v86, v86
	v_exp_f32_e32 v87, v87
	v_cvt_pk_bf16_f32 v126, v84, v85
	v_cvt_pk_bf16_f32 v127, v86, v87
	v_add_f32_e32 v215, v215, v79
	s_waitcnt lgkmcnt(4)
	v_mfma_f32_32x32x16_bf16 v[48:63], v[68:71], v[124:127], v[48:63]
	ds_read_b128 v[72:75], v219 offset:4704
	ds_read_b128 v[76:79], v219 offset:9312
	v_exp_f32_e32 v88, v88
	v_exp_f32_e32 v89, v89
	v_add_f32_e32 v209, v209, v80
	v_add_f32_e32 v211, v211, v81
	v_add_f32_e32 v213, v213, v82
	s_waitcnt lgkmcnt(5)
	v_mfma_f32_32x32x16_bf16 v[32:47], v[116:119], v[124:127], v[32:47]
	ds_read_b128 v[68:71], v219 offset:13920
	v_exp_f32_e32 v90, v90
	v_exp_f32_e32 v91, v91
	v_cvt_pk_bf16_f32 v250, v88, v89
	v_add_f32_e32 v215, v215, v83
	v_add_f32_e32 v209, v209, v84
	s_waitcnt lgkmcnt(5)
	v_mfma_f32_32x32x16_bf16 v[16:31], v[120:123], v[124:127], v[16:31]
	v_exp_f32_e32 v92, v92
	v_exp_f32_e32 v93, v93
	v_cvt_pk_bf16_f32 v251, v90, v91
	v_add_f32_e32 v211, v211, v85
	v_add_f32_e32 v213, v213, v86
	s_waitcnt lgkmcnt(4)
	v_mfma_f32_32x32x16_bf16 v[0:15], v[112:115], v[124:127], v[0:15]
	v_exp_f32_e32 v94, v94
	v_exp_f32_e32 v95, v95
	v_cvt_pk_bf16_f32 v252, v92, v93
	v_cvt_pk_bf16_f32 v253, v94, v95
	v_add_f32_e32 v215, v215, v87
	s_waitcnt lgkmcnt(3)
	v_mfma_f32_32x32x16_bf16 v[48:63], v[64:67], v[250:253], v[48:63]
	v_add_f32_e32 v209, v209, v88
	v_add_f32_e32 v211, v211, v89
	s_waitcnt lgkmcnt(2)
	v_mfma_f32_32x32x16_bf16 v[32:47], v[72:75], v[250:253], v[32:47]
	v_add_f32_e32 v213, v213, v90
	v_add_f32_e32 v215, v215, v91
	s_waitcnt lgkmcnt(1)
	v_mfma_f32_32x32x16_bf16 v[16:31], v[76:79], v[250:253], v[16:31]
	v_add_f32_e32 v209, v209, v92
	v_add_f32_e32 v211, v211, v93
	s_waitcnt lgkmcnt(0)
	v_mfma_f32_32x32x16_bf16 v[0:15], v[68:71], v[250:253], v[0:15]
	v_add_f32_e32 v213, v213, v94
	v_add_f32_e32 v215, v215, v95
	v_add_f32_e32 v209, v209, v211
	v_add_f32_e32 v213, v213, v215
	v_add_f32_e32 v209, v209, v213
	v_add_f32_e32 v205, v205, v209
